# mixer SGU epilogue: 8 bias loads hoisted up front into free VGPRs, per-step vmcnt(0) ladder removed (stores stay in flight)
# baseline (speedup 1.0000x reference)
; __device__ __forceinline__ void unpack8(const v4u w, float (&x)[8]) { x[0] = bf_lo(w.x); x[1] = bf_hi(w.x); x[2] = bf_lo(w.y); x[3] = bf_hi(w.y); x[4] = bf_lo(w.z); x[5] = bf_hi(w.z); x[6] = bf_lo(w.w); x[7] = bf_hi(w.w); }
; __device__ __forceinline__ void mixer_phase(LAS unsigned char* lds, bf16* U  , const bf16* V, const bf16* C, bf16* Bout,
;                                             const bf16* wsb, const float* sgu_b, const float* sgu_g, const bf16* pwT, const float* pool_scale, int G, int bid) {
;     ...
; #pragma unroll
;             for (int m = 0; m < 8; ++m) {
;                 const int t = 16 * m + fr; const float bias = sgu_b[g * 128 + t];
;                 bf16* up = U + (size_t)(r0 + t) * D + g * 256 + 32 * wid + 8 * fq;
;                 float x[8]; unpack8(uu[m], x);
.LBB0_689:
	v_lshl_or_b32 v96, s37, 7, v109
	v_mov_b32_e32 v97, v105
	v_lshl_add_u64 v[96:97], v[96:97], 2, s[42:43]
	global_load_dword v98, v[96:97], off
	global_load_dword v194, v[96:97], off offset:64
	global_load_dword v224, v[96:97], off offset:128
	global_load_dword v246, v[96:97], off offset:192
	global_load_dword v248, v[96:97], off offset:256
	global_load_dword v250, v[96:97], off offset:320
	global_load_dword v252, v[96:97], off offset:384
	global_load_dword v247, v[96:97], off offset:448
	s_waitcnt vmcnt(15)
	v_lshlrev_b32_e32 v100, 16, v84
	v_and_b32_e32 v101, 0xffff0000, v84
	v_lshlrev_b32_e32 v84, 16, v85
	v_and_b32_e32 v85, 0xffff0000, v85
	v_lshlrev_b32_e32 v102, 16, v86
	v_and_b32_e32 v103, 0xffff0000, v86
	v_lshlrev_b32_e32 v86, 16, v87
	v_and_b32_e32 v87, 0xffff0000, v87
	s_add_i32 s37, s37, 1
	s_cmp_eq_u32 s37, 4
	s_waitcnt vmcnt(0)
; __device__ __forceinline__ unsigned pk2(float lo, float hi) { bf16x2_t r = __builtin_convertvector((f32x2_t){lo, hi}, bf16x2_t); return __builtin_bit_cast(unsigned, r); }
; __device__ __forceinline__ void unpack8(const v4u w, float (&x)[8]) { x[0] = bf_lo(w.x); x[1] = bf_hi(w.x); x[2] = bf_lo(w.y); x[3] = bf_hi(w.y); x[4] = bf_lo(w.z); x[5] = bf_hi(w.z); x[6] = bf_lo(w.w); x[7] = bf_hi(w.w); }
; __device__ __forceinline__ void mixer_phase(LAS unsigned char* lds, bf16* U  , const bf16* V, const bf16* C, bf16* Bout,
;                                             const bf16* wsb, const float* sgu_b, const float* sgu_g, const bf16* pwT, const float* pool_scale, int G, int bid) {
;     ...
;             for (int m = 0; m < 8; ++m) {
;                 const int t = 16 * m + fr; const float bias = sgu_b[g * 128 + t];
;                 bf16* up = U + (size_t)(r0 + t) * D + g * 256 + 32 * wid + 8 * fq;
;                 float x[8]; unpack8(uu[m], x);
;                 v4u w; w.x = pk2(x[0] * (acc[m][0][0] + bias), x[1] * (acc[m][0][1] + bias)); w.y = pk2(x[2] * (acc[m][0][2] + bias), x[3] * (acc[m][0][3] + bias));
;                 w.z = pk2(x[4] * (acc[m][1][0] + bias), x[5] * (acc[m][1][1] + bias)); w.w = pk2(x[6] * (acc[m][1][2] + bias), x[7] * (acc[m][1][3] + bias));
;                 st16_wt(up, w);
;             }
	v_pk_add_f32 v[92:93], v[92:93], v[98:99] op_sel_hi:[1,0]
	v_pk_add_f32 v[94:95], v[94:95], v[98:99] op_sel_hi:[1,0]
	v_pk_add_f32 v[88:89], v[88:89], v[98:99] op_sel_hi:[1,0]
	v_pk_add_f32 v[90:91], v[90:91], v[98:99] op_sel_hi:[1,0]
	v_pk_mul_f32 v[92:93], v[92:93], v[100:101]
	v_pk_mul_f32 v[94:95], v[94:95], v[84:85]
	v_pk_mul_f32 v[88:89], v[88:89], v[102:103]
	v_pk_mul_f32 v[90:91], v[90:91], v[86:87]
	v_cvt_pk_bf16_f32 v84, v92, v93
	v_cvt_pk_bf16_f32 v85, v94, v95
	v_cvt_pk_bf16_f32 v86, v88, v89
	v_cvt_pk_bf16_f32 v87, v90, v91
	global_store_dwordx4 v[192:193], v[84:87], off
	v_lshlrev_b32_e32 v88, 16, v72
	v_and_b32_e32 v89, 0xffff0000, v72
	v_lshlrev_b32_e32 v72, 16, v73
	v_and_b32_e32 v73, 0xffff0000, v73
	v_lshlrev_b32_e32 v90, 16, v74
	v_and_b32_e32 v91, 0xffff0000, v74
	v_lshlrev_b32_e32 v74, 16, v75
	v_and_b32_e32 v75, 0xffff0000, v75
	v_lshl_add_u64 v[86:87], v[190:191], 0, v[176:177]
	v_pk_add_f32 v[80:81], v[80:81], v[194:195] op_sel_hi:[1,0]
	v_pk_add_f32 v[82:83], v[82:83], v[194:195] op_sel_hi:[1,0]
	v_pk_add_f32 v[76:77], v[76:77], v[194:195] op_sel_hi:[1,0]
	v_pk_add_f32 v[78:79], v[78:79], v[194:195] op_sel_hi:[1,0]
	v_pk_mul_f32 v[80:81], v[80:81], v[88:89]
	v_pk_mul_f32 v[82:83], v[82:83], v[72:73]
	v_pk_mul_f32 v[76:77], v[76:77], v[90:91]
	v_pk_mul_f32 v[78:79], v[78:79], v[74:75]
	v_cvt_pk_bf16_f32 v72, v80, v81
	v_cvt_pk_bf16_f32 v73, v82, v83
	v_cvt_pk_bf16_f32 v74, v76, v77
	v_cvt_pk_bf16_f32 v75, v78, v79
	global_store_dwordx4 v[86:87], v[72:75], off
	v_lshlrev_b32_e32 v76, 16, v60
	v_and_b32_e32 v77, 0xffff0000, v60
	v_lshlrev_b32_e32 v60, 16, v61
	v_and_b32_e32 v61, 0xffff0000, v61
	v_lshlrev_b32_e32 v78, 16, v62
	v_and_b32_e32 v79, 0xffff0000, v62
	v_lshlrev_b32_e32 v62, 16, v63
	v_and_b32_e32 v63, 0xffff0000, v63
	v_lshl_add_u64 v[74:75], v[190:191], 0, v[178:179]
	v_pk_add_f32 v[68:69], v[68:69], v[224:225] op_sel_hi:[1,0]
	v_pk_add_f32 v[70:71], v[70:71], v[224:225] op_sel_hi:[1,0]
	v_pk_add_f32 v[64:65], v[64:65], v[224:225] op_sel_hi:[1,0]
	v_pk_add_f32 v[66:67], v[66:67], v[224:225] op_sel_hi:[1,0]
	v_pk_mul_f32 v[68:69], v[68:69], v[76:77]
	v_pk_mul_f32 v[70:71], v[70:71], v[60:61]
	v_pk_mul_f32 v[64:65], v[64:65], v[78:79]
	v_pk_mul_f32 v[66:67], v[66:67], v[62:63]
	v_cvt_pk_bf16_f32 v60, v68, v69
	v_cvt_pk_bf16_f32 v61, v70, v71
	v_cvt_pk_bf16_f32 v62, v64, v65
	v_cvt_pk_bf16_f32 v63, v66, v67
	global_store_dwordx4 v[74:75], v[60:63], off
	v_lshlrev_b32_e32 v64, 16, v48
	v_and_b32_e32 v65, 0xffff0000, v48
	v_lshlrev_b32_e32 v48, 16, v49
	v_and_b32_e32 v49, 0xffff0000, v49
	v_lshlrev_b32_e32 v66, 16, v50
	v_and_b32_e32 v67, 0xffff0000, v50
	v_lshlrev_b32_e32 v50, 16, v51
	v_and_b32_e32 v51, 0xffff0000, v51
	v_lshl_add_u64 v[62:63], v[190:191], 0, v[180:181]
	v_pk_add_f32 v[56:57], v[56:57], v[246:247] op_sel_hi:[1,0]
	v_pk_add_f32 v[58:59], v[58:59], v[246:247] op_sel_hi:[1,0]
	v_pk_add_f32 v[52:53], v[52:53], v[246:247] op_sel_hi:[1,0]
	v_pk_add_f32 v[54:55], v[54:55], v[246:247] op_sel_hi:[1,0]
	v_pk_mul_f32 v[56:57], v[56:57], v[64:65]
	v_pk_mul_f32 v[58:59], v[58:59], v[48:49]
	v_pk_mul_f32 v[52:53], v[52:53], v[66:67]
	v_pk_mul_f32 v[54:55], v[54:55], v[50:51]
	v_cvt_pk_bf16_f32 v48, v56, v57
	v_cvt_pk_bf16_f32 v49, v58, v59
	v_cvt_pk_bf16_f32 v50, v52, v53
	v_cvt_pk_bf16_f32 v51, v54, v55
	global_store_dwordx4 v[62:63], v[48:51], off
	v_lshlrev_b32_e32 v52, 16, v36
	v_and_b32_e32 v53, 0xffff0000, v36
	v_lshlrev_b32_e32 v36, 16, v37
	v_and_b32_e32 v37, 0xffff0000, v37
	v_lshlrev_b32_e32 v54, 16, v38
	v_and_b32_e32 v55, 0xffff0000, v38
	v_lshlrev_b32_e32 v38, 16, v39
	v_and_b32_e32 v39, 0xffff0000, v39
	v_lshl_add_u64 v[50:51], v[190:191], 0, v[182:183]
	v_pk_add_f32 v[44:45], v[44:45], v[248:249] op_sel_hi:[1,0]
	v_pk_add_f32 v[46:47], v[46:47], v[248:249] op_sel_hi:[1,0]
	v_pk_add_f32 v[40:41], v[40:41], v[248:249] op_sel_hi:[1,0]
	v_pk_add_f32 v[42:43], v[42:43], v[248:249] op_sel_hi:[1,0]
	v_pk_mul_f32 v[44:45], v[44:45], v[52:53]
	v_pk_mul_f32 v[46:47], v[46:47], v[36:37]
	v_pk_mul_f32 v[40:41], v[40:41], v[54:55]
	v_pk_mul_f32 v[42:43], v[42:43], v[38:39]
	v_cvt_pk_bf16_f32 v36, v44, v45
	v_cvt_pk_bf16_f32 v37, v46, v47
	v_cvt_pk_bf16_f32 v38, v40, v41
	v_cvt_pk_bf16_f32 v39, v42, v43
	global_store_dwordx4 v[50:51], v[36:39], off
	v_lshlrev_b32_e32 v40, 16, v28
	v_and_b32_e32 v41, 0xffff0000, v28
	v_lshlrev_b32_e32 v28, 16, v29
	v_and_b32_e32 v29, 0xffff0000, v29
	v_lshlrev_b32_e32 v42, 16, v30
	v_and_b32_e32 v43, 0xffff0000, v30
	v_lshlrev_b32_e32 v30, 16, v31
	v_and_b32_e32 v31, 0xffff0000, v31
	v_lshl_add_u64 v[38:39], v[190:191], 0, v[184:185]
	v_pk_add_f32 v[32:33], v[32:33], v[250:251] op_sel_hi:[1,0]
	v_pk_add_f32 v[34:35], v[34:35], v[250:251] op_sel_hi:[1,0]
	v_pk_add_f32 v[24:25], v[24:25], v[250:251] op_sel_hi:[1,0]
	v_pk_add_f32 v[26:27], v[26:27], v[250:251] op_sel_hi:[1,0]
	v_pk_mul_f32 v[32:33], v[32:33], v[40:41]
	v_pk_mul_f32 v[28:29], v[34:35], v[28:29]
	v_pk_mul_f32 v[34:35], v[24:25], v[42:43]
	v_pk_mul_f32 v[30:31], v[26:27], v[30:31]
	v_cvt_pk_bf16_f32 v24, v32, v33
	v_cvt_pk_bf16_f32 v25, v28, v29
	v_cvt_pk_bf16_f32 v26, v34, v35
	v_cvt_pk_bf16_f32 v27, v30, v31
	global_store_dwordx4 v[38:39], v[24:27], off
	v_lshlrev_b32_e32 v28, 16, v12
	v_and_b32_e32 v29, 0xffff0000, v12
	v_lshlrev_b32_e32 v12, 16, v13
	v_and_b32_e32 v13, 0xffff0000, v13
	v_lshlrev_b32_e32 v30, 16, v14
	v_and_b32_e32 v31, 0xffff0000, v14
	v_lshlrev_b32_e32 v14, 16, v15
	v_and_b32_e32 v15, 0xffff0000, v15
	v_lshl_add_u64 v[26:27], v[190:191], 0, v[186:187]
	v_pk_add_f32 v[20:21], v[20:21], v[252:253] op_sel_hi:[1,0]
	v_pk_add_f32 v[22:23], v[22:23], v[252:253] op_sel_hi:[1,0]
	v_pk_add_f32 v[16:17], v[16:17], v[252:253] op_sel_hi:[1,0]
	v_pk_add_f32 v[18:19], v[18:19], v[252:253] op_sel_hi:[1,0]
	v_pk_mul_f32 v[20:21], v[20:21], v[28:29]
	v_pk_mul_f32 v[22:23], v[22:23], v[12:13]
	v_pk_mul_f32 v[16:17], v[16:17], v[30:31]
	v_pk_mul_f32 v[18:19], v[18:19], v[14:15]
	v_cvt_pk_bf16_f32 v12, v20, v21
	v_cvt_pk_bf16_f32 v13, v22, v23
	v_cvt_pk_bf16_f32 v14, v16, v17
	v_cvt_pk_bf16_f32 v15, v18, v19
	global_store_dwordx4 v[26:27], v[12:15], off
	v_lshlrev_b32_e32 v16, 16, v4
	v_and_b32_e32 v17, 0xffff0000, v4
	v_lshlrev_b32_e32 v4, 16, v5
	v_and_b32_e32 v5, 0xffff0000, v5
	v_lshlrev_b32_e32 v18, 16, v6
	v_and_b32_e32 v19, 0xffff0000, v6
	v_lshlrev_b32_e32 v6, 16, v7
	v_and_b32_e32 v7, 0xffff0000, v7
	v_lshl_add_u64 v[14:15], v[190:191], 0, v[188:189]
	v_add_f32_e32 v8, v8, v247
	v_add_f32_e32 v9, v9, v247
	v_add_f32_e32 v10, v10, v247
	v_add_f32_e32 v11, v11, v247
	v_add_f32_e32 v0, v0, v247
	v_add_f32_e32 v1, v1, v247
	v_add_f32_e32 v2, v2, v247
	v_add_f32_e32 v3, v3, v247
	v_pk_mul_f32 v[8:9], v[8:9], v[16:17]
	v_pk_mul_f32 v[4:5], v[10:11], v[4:5]
	v_pk_mul_f32 v[10:11], v[0:1], v[18:19]
	v_pk_mul_f32 v[6:7], v[2:3], v[6:7]
	v_cvt_pk_bf16_f32 v0, v8, v9
	v_cvt_pk_bf16_f32 v1, v4, v5
	v_cvt_pk_bf16_f32 v2, v10, v11
	v_cvt_pk_bf16_f32 v3, v6, v7
	global_store_dwordx4 v[14:15], v[0:3], off
	s_barrier
	s_cbranch_scc1 .LBB0_704
